# prep w_in transpose: lane->(n,k-group) mapping changed so 8 consecutive lanes write one full 128-byte line of W1T (coalesced stores)
# speedup vs baseline: 1.0199x; 1.0044x over previous
.Lmy_w1_loop:
	v_lshrrev_b32_e32 v15, 3, v9
	v_and_b32_e32 v13, 7, v9
	v_mul_hi_i32 v1, v15, s1
	v_lshrrev_b32_e32 v2, 31, v1
	v_ashrrev_i32_e32 v1, 10, v1
	v_add_u32_e32 v1, v1, v2
	v_mul_i32_i24_e32 v2, 0x1200, v1
	v_sub_u32_e32 v14, v15, v2
	v_lshl_or_b32 v1, v1, 3, v13
	v_lshlrev_b32_e32 v12, 3, v1
	v_ashrrev_i32_e32 v15, 31, v14
	v_ashrrev_i32_e32 v13, 31, v12
	v_lshl_add_u64 v[16:17], v[14:15], 2, s[58:59]
	v_mul_hi_i32_i24_e32 v3, 0x4800, v12
	v_mul_i32_i24_e32 v2, 0x4800, v12
	v_lshl_add_u64 v[2:3], v[16:17], 0, v[2:3]
	v_lshl_add_u64 v[18:19], v[12:13], 2, s[56:57]
	global_load_dword v26, v[2:3], off
	v_lshl_add_u64 v[2:3], v[2:3], 0, s[28:29]
	global_load_dword v27, v[2:3], off
	v_lshl_add_u64 v[2:3], v[2:3], 0, s[28:29]
	global_load_dword v28, v[2:3], off
	v_lshl_add_u64 v[2:3], v[2:3], 0, s[28:29]
	global_load_dword v29, v[2:3], off
	v_lshl_add_u64 v[2:3], v[2:3], 0, s[28:29]
	global_load_dword v30, v[2:3], off
	v_lshl_add_u64 v[2:3], v[2:3], 0, s[28:29]
	global_load_dword v31, v[2:3], off
	v_lshl_add_u64 v[2:3], v[2:3], 0, s[28:29]
	global_load_dword v32, v[2:3], off
	v_lshl_add_u64 v[2:3], v[2:3], 0, s[28:29]
	global_load_dword v33, v[2:3], off
	global_load_dwordx4 v[34:37], v[18:19], off
	global_load_dwordx4 v[38:41], v[18:19], off offset:16
	v_lshlrev_b64 v[6:7], 11, v[14:15]
	v_add_u32_e32 v9, s0, v9
	v_lshl_add_u64 v[6:7], s[16:17], 0, v[6:7]
	v_cmp_lt_i32_e32 vcc, s2, v9
	v_lshl_add_u64 v[6:7], v[12:13], 1, v[6:7]
	s_or_b64 s[18:19], vcc, s[18:19]
	s_waitcnt vmcnt(0)
	v_mul_f32_e32 v26, v26, v34
	v_mul_f32_e32 v27, v27, v35
	v_mul_f32_e32 v28, v28, v36
	v_mul_f32_e32 v29, v29, v37
	v_mul_f32_e32 v30, v30, v38
	v_mul_f32_e32 v31, v31, v39
	v_mul_f32_e32 v32, v32, v40
	v_mul_f32_e32 v33, v33, v41
	v_cvt_pk_bf16_f32 v2, v26, v27
	v_cvt_pk_bf16_f32 v3, v28, v29
	v_cvt_pk_bf16_f32 v4, v30, v31
	v_cvt_pk_bf16_f32 v5, v32, v33
	global_store_dwordx4 v[6:7], v[2:5], off
	s_andn2_b64 exec, exec, s[18:19]
	s_cbranch_execnz .Lmy_w1_loop
	s_branch .LBB0_30
